# v19 plus diff-attention epilogue: first 8 map-1 stash reloads prefetched together with counted vmcnt
# baseline (speedup 1.0000x reference)
;     ...
;       const float inv2 = p.lam[layer] / l;
;       float ss = 0.f;
; #pragma unroll
;       for (int d = 0; d < 4; ++d)
; #pragma unroll
;         for (int g = 0; g < 4; ++g) {
;           const float4 a = *(const float4*)(d1 + 32 * d + 8 * g);
;           o[d][4 * g] = a.x - o[d][4 * g] * inv2; o[d][4 * g + 1] = a.y - o[d][4 * g + 1] * inv2;
;           o[d][4 * g + 2] = a.z - o[d][4 * g + 2] * inv2; o[d][4 * g + 3] = a.w - o[d][4 * g + 3] * inv2;
;           ss += o[d][4 * g] * o[d][4 * g] + o[d][4 * g + 1] * o[d][4 * g + 1] + o[d][4 * g + 2] * o[d][4 * g + 2] + o[d][4 * g + 3] * o[d][4 * g + 3];
;         }
.LBB0_866:
	global_load_dword v34, v[212:213], off
	ds_bpermute_b32 v0, v162, v155
	s_waitcnt lgkmcnt(0)
	v_add_f32_e32 v0, v155, v0
	s_waitcnt vmcnt(0)
	v_div_scale_f32 v35, s[0:1], v0, v0, v34
	v_rcp_f32_e32 v36, v35
	s_mov_b32 s0, 0x800000
	v_fma_f32 v37, -v35, v36, 1.0
	v_fmac_f32_e32 v36, v37, v36
	v_div_scale_f32 v37, vcc, v34, v0, v34
	v_mul_f32_e32 v38, v37, v36
	v_fma_f32 v39, -v35, v38, v37
	v_fmac_f32_e32 v38, v39, v36
	v_fma_f32 v35, -v35, v38, v37
	v_div_fmas_f32 v35, v35, v36, v38
	v_div_fixup_f32 v0, v35, v0, v34
	global_load_dwordx4 v[216:219], v[150:151], off
	global_load_dwordx4 v[220:223], v[150:151], off offset:32
	global_load_dwordx4 v[224:227], v[150:151], off offset:64
	global_load_dwordx4 v[228:231], v[150:151], off offset:96
	global_load_dwordx4 v[232:235], v[150:151], off offset:128
	global_load_dwordx4 v[236:239], v[150:151], off offset:160
	global_load_dwordx4 v[240:243], v[150:151], off offset:192
	global_load_dwordx4 v[244:247], v[150:151], off offset:224
	s_waitcnt vmcnt(7)
	v_mov_b32_e32 v34, v216
	v_mov_b32_e32 v35, v217
	v_mov_b32_e32 v36, v218
	v_mov_b32_e32 v37, v219
	v_pk_fma_f32 v[88:89], v[66:67], v[0:1], v[34:35] op_sel_hi:[1,0,1] neg_lo:[1,0,0] neg_hi:[1,0,0]
	v_pk_fma_f32 v[90:91], v[68:69], v[0:1], v[36:37] op_sel_hi:[1,0,1] neg_lo:[1,0,0] neg_hi:[1,0,0]
	v_pk_mul_f32 v[94:95], v[88:89], v[88:89]
	v_pk_mul_f32 v[92:93], v[90:91], v[90:91]
	s_waitcnt vmcnt(6)
	v_mov_b32_e32 v34, v220
	v_mov_b32_e32 v35, v221
	v_mov_b32_e32 v36, v222
	v_mov_b32_e32 v37, v223
	v_pk_fma_f32 v[86:87], v[70:71], v[0:1], v[34:35] op_sel_hi:[1,0,1] neg_lo:[1,0,0] neg_hi:[1,0,0]
	v_pk_fma_f32 v[84:85], v[72:73], v[0:1], v[36:37] op_sel_hi:[1,0,1] neg_lo:[1,0,0] neg_hi:[1,0,0]
	v_pk_mul_f32 v[98:99], v[86:87], v[86:87]
	v_pk_mul_f32 v[96:97], v[84:85], v[84:85]
	s_waitcnt vmcnt(5)
	v_mov_b32_e32 v34, v224
	v_mov_b32_e32 v35, v225
	v_mov_b32_e32 v36, v226
	v_mov_b32_e32 v37, v227
	v_pk_fma_f32 v[82:83], v[74:75], v[0:1], v[34:35] op_sel_hi:[1,0,1] neg_lo:[1,0,0] neg_hi:[1,0,0]
	v_pk_fma_f32 v[74:75], v[76:77], v[0:1], v[36:37] op_sel_hi:[1,0,1] neg_lo:[1,0,0] neg_hi:[1,0,0]
	v_pk_mul_f32 v[100:101], v[82:83], v[82:83]
	v_pk_mul_f32 v[76:77], v[74:75], v[74:75]
	s_waitcnt vmcnt(4)
	v_mov_b32_e32 v34, v228
	v_mov_b32_e32 v35, v229
	v_mov_b32_e32 v36, v230
	v_mov_b32_e32 v37, v231
	v_pk_fma_f32 v[72:73], v[78:79], v[0:1], v[34:35] op_sel_hi:[1,0,1] neg_lo:[1,0,0] neg_hi:[1,0,0]
	v_pk_fma_f32 v[70:71], v[80:81], v[0:1], v[36:37] op_sel_hi:[1,0,1] neg_lo:[1,0,0] neg_hi:[1,0,0]
	v_pk_mul_f32 v[80:81], v[72:73], v[72:73]
	v_pk_mul_f32 v[78:79], v[70:71], v[70:71]
	s_waitcnt vmcnt(3)
	v_mov_b32_e32 v34, v232
	v_mov_b32_e32 v35, v233
	v_mov_b32_e32 v36, v234
	v_mov_b32_e32 v37, v235
	v_pk_fma_f32 v[68:69], v[50:51], v[0:1], v[34:35] op_sel_hi:[1,0,1] neg_lo:[1,0,0] neg_hi:[1,0,0]
	v_pk_fma_f32 v[66:67], v[52:53], v[0:1], v[36:37] op_sel_hi:[1,0,1] neg_lo:[1,0,0] neg_hi:[1,0,0]
	v_pk_mul_f32 v[104:105], v[68:69], v[68:69]
	v_pk_mul_f32 v[102:103], v[66:67], v[66:67]
	s_waitcnt vmcnt(2)
	v_mov_b32_e32 v34, v236
	v_mov_b32_e32 v35, v237
	v_mov_b32_e32 v36, v238
	v_mov_b32_e32 v37, v239
	v_pk_fma_f32 v[52:53], v[54:55], v[0:1], v[34:35] op_sel_hi:[1,0,1] neg_lo:[1,0,0] neg_hi:[1,0,0]
	v_pk_fma_f32 v[50:51], v[56:57], v[0:1], v[36:37] op_sel_hi:[1,0,1] neg_lo:[1,0,0] neg_hi:[1,0,0]
	v_pk_mul_f32 v[56:57], v[52:53], v[52:53]
	v_pk_mul_f32 v[54:55], v[50:51], v[50:51]
	s_waitcnt vmcnt(1)
	v_mov_b32_e32 v34, v240
	v_mov_b32_e32 v35, v241
	v_mov_b32_e32 v36, v242
	v_mov_b32_e32 v37, v243
	v_pk_fma_f32 v[48:49], v[58:59], v[0:1], v[34:35] op_sel_hi:[1,0,1] neg_lo:[1,0,0] neg_hi:[1,0,0]
	v_pk_fma_f32 v[44:45], v[60:61], v[0:1], v[36:37] op_sel_hi:[1,0,1] neg_lo:[1,0,0] neg_hi:[1,0,0]
	v_mov_b32_e32 v40, v49
	s_waitcnt vmcnt(0)
	v_mov_b32_e32 v34, v244
	v_mov_b32_e32 v35, v245
	v_mov_b32_e32 v36, v246
	v_mov_b32_e32 v37, v247
	v_pk_fma_f32 v[38:39], v[62:63], v[0:1], v[34:35] op_sel_hi:[1,0,1] neg_lo:[1,0,0] neg_hi:[1,0,0]
	s_nop 0
	v_mov_b32_e32 v41, v39
	v_pk_fma_f32 v[36:37], v[64:65], v[0:1], v[36:37] op_sel_hi:[1,0,1] neg_lo:[1,0,0] neg_hi:[1,0,0]
	v_mov_b32_e32 v34, v48
	v_mov_b32_e32 v35, v38
	v_pk_mul_f32 v[40:41], v[40:41], v[40:41]
	global_load_dwordx4 v[60:63], v[150:151], off offset:384
	v_pk_fma_f32 v[34:35], v[34:35], v[34:35], v[40:41]
	v_mov_b32_e32 v40, v44
	v_mov_b32_e32 v41, v36
	v_pk_fma_f32 v[34:35], v[40:41], v[40:41], v[34:35]
	v_mov_b32_e32 v40, v45
	v_mov_b32_e32 v41, v37
	v_pk_fma_f32 v[58:59], v[40:41], v[40:41], v[34:35]
	global_load_dwordx4 v[40:43], v[150:151], off offset:256
	s_waitcnt vmcnt(0)
	v_pk_fma_f32 v[46:47], v[18:19], v[0:1], v[40:41] op_sel_hi:[1,0,1] neg_lo:[1,0,0] neg_hi:[1,0,0]
	v_pk_fma_f32 v[42:43], v[20:21], v[0:1], v[42:43] op_sel_hi:[1,0,1] neg_lo:[1,0,0] neg_hi:[1,0,0]
	global_load_dwordx4 v[18:21], v[150:151], off offset:288
	s_waitcnt vmcnt(0)
	v_pk_fma_f32 v[34:35], v[22:23], v[0:1], v[18:19] op_sel_hi:[1,0,1] neg_lo:[1,0,0] neg_hi:[1,0,0]
	v_pk_fma_f32 v[22:23], v[24:25], v[0:1], v[20:21] op_sel_hi:[1,0,1] neg_lo:[1,0,0] neg_hi:[1,0,0]
	v_mov_b32_e32 v20, v47
	v_mov_b32_e32 v21, v35
	v_mov_b32_e32 v18, v46
	v_mov_b32_e32 v19, v34
	v_pk_mul_f32 v[20:21], v[20:21], v[20:21]
	s_nop 0
	v_pk_fma_f32 v[18:19], v[18:19], v[18:19], v[20:21]
	v_mov_b32_e32 v20, v42
	v_mov_b32_e32 v21, v22
	v_pk_fma_f32 v[18:19], v[20:21], v[20:21], v[18:19]
	v_mov_b32_e32 v20, v43
	v_mov_b32_e32 v21, v23
	v_pk_fma_f32 v[64:65], v[20:21], v[20:21], v[18:19]
	global_load_dwordx4 v[18:21], v[150:151], off offset:320
	s_waitcnt vmcnt(0)
; DI void store_gated(const Params& p, int R, int colbase, f32x16 (&o)[4], float mult, const float* wv, int h) {
;     ...
;       const int dv = 32 * d0 + 8 * g + 4 * h;
;       const size_t off = (size_t)R * DM + colbase + dv;
;       const u32x2 gg = *(const u32x2*)(p.Gs + off);
;       float v0 = o[d0][4 * g] * mult, v1 = o[d0][4 * g + 1] * mult, v2 = o[d0][4 * g + 2] * mult, v3 = o[d0][4 * g + 3] * mult;
;       if (wv) { v0 *= wv[dv]; v1 *= wv[dv + 1]; v2 *= wv[dv + 2]; v3 *= wv[dv + 3]; }
;     ...
;       float ss = 0.f;
; #pragma unroll
;       for (int d = 0; d < 4; ++d)
; #pragma unroll
;         for (int g = 0; g < 4; ++g) {
;           const float4 a = *(const float4*)(d1 + 32 * d + 8 * g);
;           o[d][4 * g] = a.x - o[d][4 * g] * inv2; o[d][4 * g + 1] = a.y - o[d][4 * g + 1] * inv2;
;           o[d][4 * g + 2] = a.z - o[d][4 * g + 2] * inv2; o[d][4 * g + 3] = a.w - o[d][4 * g + 3] * inv2;
;           ss += o[d][4 * g] * o[d][4 * g] + o[d][4 * g + 1] * o[d][4 * g + 1] + o[d][4 * g + 2] * o[d][4 * g + 2] + o[d][4 * g + 3] * o[d][4 * g + 3];
;         }
;       ss += __shfl_xor(ss, 32);
;       const float mult = rsqrtf(ss * (1.f / 128.f) + EPS) * p.lam[4 + layer];
;       store_gated(p, q0 + wid * 32 + r32, 1408 + hd * 128, o, mult, p.subln + layer * 128, h);
	v_pk_fma_f32 v[40:41], v[26:27], v[0:1], v[18:19] op_sel_hi:[1,0,1] neg_lo:[1,0,0] neg_hi:[1,0,0]
	v_pk_fma_f32 v[28:29], v[28:29], v[0:1], v[20:21] op_sel_hi:[1,0,1] neg_lo:[1,0,0] neg_hi:[1,0,0]
	global_load_dwordx4 v[18:21], v[150:151], off offset:352
	v_mov_b32_e32 v26, v41
	s_waitcnt vmcnt(0)
	v_pk_fma_f32 v[24:25], v[30:31], v[0:1], v[18:19] op_sel_hi:[1,0,1] neg_lo:[1,0,0] neg_hi:[1,0,0]
	v_pk_fma_f32 v[18:19], v[32:33], v[0:1], v[20:21] op_sel_hi:[1,0,1] neg_lo:[1,0,0] neg_hi:[1,0,0]
	v_pk_fma_f32 v[32:33], v[2:3], v[0:1], v[60:61] op_sel_hi:[1,0,1] neg_lo:[1,0,0] neg_hi:[1,0,0]
	v_pk_fma_f32 v[30:31], v[4:5], v[0:1], v[62:63] op_sel_hi:[1,0,1] neg_lo:[1,0,0] neg_hi:[1,0,0]
	global_load_dwordx4 v[2:5], v[150:151], off offset:416
	v_mov_b32_e32 v27, v25
	v_mov_b32_e32 v20, v40
	v_mov_b32_e32 v21, v24
	v_pk_mul_f32 v[26:27], v[26:27], v[26:27]
	s_nop 0
	v_pk_fma_f32 v[20:21], v[20:21], v[20:21], v[26:27]
	v_mov_b32_e32 v26, v28
	v_mov_b32_e32 v27, v18
	v_pk_fma_f32 v[20:21], v[26:27], v[26:27], v[20:21]
	v_mov_b32_e32 v26, v29
	v_mov_b32_e32 v27, v19
	v_pk_fma_f32 v[106:107], v[26:27], v[26:27], v[20:21]
	s_waitcnt vmcnt(0)
	v_pk_fma_f32 v[26:27], v[6:7], v[0:1], v[2:3] op_sel_hi:[1,0,1] neg_lo:[1,0,0] neg_hi:[1,0,0]
	v_pk_fma_f32 v[20:21], v[8:9], v[0:1], v[4:5] op_sel_hi:[1,0,1] neg_lo:[1,0,0] neg_hi:[1,0,0]
	v_mov_b32_e32 v4, v33
	v_mov_b32_e32 v5, v27
	v_mov_b32_e32 v2, v32
	v_mov_b32_e32 v3, v26
	v_pk_mul_f32 v[4:5], v[4:5], v[4:5]
	s_nop 0
	v_pk_fma_f32 v[2:3], v[2:3], v[2:3], v[4:5]
	v_mov_b32_e32 v4, v30
	v_mov_b32_e32 v5, v20
	v_pk_fma_f32 v[2:3], v[4:5], v[4:5], v[2:3]
	v_mov_b32_e32 v4, v31
	v_mov_b32_e32 v5, v21
	v_pk_fma_f32 v[60:61], v[4:5], v[4:5], v[2:3]
	global_load_dwordx4 v[2:5], v[150:151], off offset:448
	s_waitcnt vmcnt(0)
	v_pk_fma_f32 v[8:9], v[10:11], v[0:1], v[2:3] op_sel_hi:[1,0,1] neg_lo:[1,0,0] neg_hi:[1,0,0]
	v_pk_fma_f32 v[6:7], v[12:13], v[0:1], v[4:5] op_sel_hi:[1,0,1] neg_lo:[1,0,0] neg_hi:[1,0,0]
	global_load_dwordx4 v[10:13], v[150:151], off offset:480
	s_waitcnt vmcnt(0)
	v_pk_fma_f32 v[4:5], v[14:15], v[0:1], v[10:11] op_sel_hi:[1,0,1] neg_lo:[1,0,0] neg_hi:[1,0,0]
	v_pk_fma_f32 v[2:3], v[16:17], v[0:1], v[12:13] op_sel_hi:[1,0,1] neg_lo:[1,0,0] neg_hi:[1,0,0]
	v_mov_b32_e32 v12, v9
	v_mov_b32_e32 v13, v5
	v_mov_b32_e32 v10, v8
	v_mov_b32_e32 v11, v4
	v_pk_mul_f32 v[12:13], v[12:13], v[12:13]
	v_add_f32_e32 v0, v98, v99
	v_pk_fma_f32 v[10:11], v[10:11], v[10:11], v[12:13]
	v_mov_b32_e32 v12, v6
	v_mov_b32_e32 v13, v2
	v_pk_fma_f32 v[10:11], v[12:13], v[12:13], v[10:11]
	v_mov_b32_e32 v12, v7
	v_mov_b32_e32 v13, v3
	v_pk_fma_f32 v[10:11], v[12:13], v[12:13], v[10:11]
	v_add_f32_e32 v12, v94, v95
	v_add_f32_e32 v0, v96, v0
	v_add_f32_e32 v12, v92, v12
	v_add_f32_e32 v0, v97, v0
	v_add_f32_e32 v12, v93, v12
	v_add_f32_e32 v0, v12, v0
	v_add_f32_e32 v12, v100, v101
	v_add_f32_e32 v12, v76, v12
	v_add_f32_e32 v12, v77, v12
	v_add_f32_e32 v0, v0, v12
	v_add_f32_e32 v12, v80, v81
	v_add_f32_e32 v12, v78, v12
	v_add_f32_e32 v12, v79, v12
	v_add_f32_e32 v0, v0, v12
	v_add_f32_e32 v12, v104, v105
	v_add_f32_e32 v12, v102, v12
	v_add_f32_e32 v12, v103, v12
	v_add_f32_e32 v0, v0, v12
	v_add_f32_e32 v12, v56, v57
	v_add_f32_e32 v12, v54, v12
	v_add_f32_e32 v12, v55, v12
	v_add_f32_e32 v0, v0, v12
	v_add_f32_e32 v0, v0, v58
	v_add_f32_e32 v0, v0, v59
	v_add_f32_e32 v0, v0, v64
	v_add_f32_e32 v0, v0, v65
	v_add_f32_e32 v0, v0, v106
	v_add_f32_e32 v0, v0, v107
	v_add_f32_e32 v0, v0, v60
	v_add_f32_e32 v0, v0, v61
	v_add_f32_e32 v0, v0, v10
	v_add_f32_e32 v0, v0, v11
	ds_bpermute_b32 v10, v162, v0
	s_waitcnt lgkmcnt(0)
	v_add_f32_e32 v0, v0, v10
	v_fmamk_f32 v0, v0, 0x3c000000, v187
	v_cmp_gt_f32_e32 vcc, s0, v0
	v_mul_f32_e32 v10, 0x4b800000, v0
	s_lshl_b32 s0, s8, 7
	v_cndmask_b32_e32 v0, v0, v10, vcc
	v_rsq_f32_e32 v0, v0
	s_ashr_i32 s1, s0, 31
	v_mul_f32_e32 v10, 0x45800000, v0
	v_cndmask_b32_e32 v0, v0, v10, vcc
	global_load_dword v10, v[212:213], off offset:16
	s_waitcnt vmcnt(0)
	v_mul_f32_e32 v10, v10, v0
	v_add_u32_e32 v0, s9, v144
	v_or_b32_e32 v12, v0, v193
	v_ashrrev_i32_e32 v13, 31, v12
	v_lshlrev_b64 v[12:13], 11, v[12:13]
	v_lshl_add_u64 v[12:13], v[12:13], 0, s[0:1]
	v_readlane_b32 s8, v252, 2
	v_or_b32_e32 v16, v12, v145
	v_mov_b32_e32 v17, v13
	v_readlane_b32 s10, v252, 4
	v_readlane_b32 s11, v252, 5
	v_readlane_b32 s0, v254, 3
	v_readlane_b32 s1, v254, 4
	v_lshl_add_u64 v[14:15], v[16:17], 1, s[10:11]
	global_load_dwordx2 v[54:55], v[14:15], off offset:2816
	v_pk_mul_f32 v[58:59], v[88:89], v[10:11] op_sel_hi:[1,0]
	v_pk_mul_f32 v[56:57], v[90:91], v[10:11] op_sel_hi:[1,0]
	s_and_b64 vcc, exec, s[0:1]
	v_lshlrev_b32_e32 v14, 2, v145
	v_readlane_b32 s9, v252, 3
	s_cbranch_vccz .LBB0_868
	v_mov_b32_e32 v15, v1
	v_lshl_add_u64 v[60:61], v[214:215], 0, v[14:15]
	global_load_dwordx4 v[60:63], v[60:61], off
	s_waitcnt vmcnt(0)
	v_pk_mul_f32 v[58:59], v[58:59], v[60:61]
	v_pk_mul_f32 v[56:57], v[56:57], v[62:63]
